# P0a adaLN: batched silu(c) staging loads (6 in flight) and software-pipelined weight loop (2 k-trips in flight)
# speedup vs baseline: 1.0176x; 1.0022x over previous
.LBB0_16:
	s_bitcmp1_b32 s44, 0
	s_cselect_b32 s22, 18, 0
	s_barrier
	s_and_saveexec_b64 s[18:19], vcc
	s_cbranch_execz .LBB0_23
	v_mov_b32_e32 v182, s6
	v_mov_b32_e32 v183, s7
	s_add_u32 s98, s10, 0xffffc000
	s_addc_u32 s99, s11, -1
	v_mov_b32_e32 v184, s98
	v_mov_b32_e32 v185, s99
	v_mov_b32_e32 v4, v40
	s_mov_b32 s98, 0
.Lsilu_outer:
	v_mov_b32_e32 v232, v4
	v_ashrrev_i32_e32 v233, 10, v232
	v_and_b32_e32 v232, 0x3ff, v232
	v_mul_u32_u24_e32 v226, 0x50, v232
	v_lshl_add_u32 v214, v233, 2, v226
	v_add_u32_e32 v233, s22, v233
	v_cmp_lt_i32_e64 s[20:21], 3, v233
	v_lshl_or_b32 v190, v233, 10, v232
	v_mov_b32_e32 v191, 0
	v_cndmask_b32_e64 v192, v182, v184, s[20:21]
	v_cndmask_b32_e64 v193, v183, v185, s[20:21]
	v_lshl_add_u64 v[192:193], v[190:191], 2, v[192:193]
	global_load_dword v220, v[192:193], off
	v_add_u32_e32 v232, 0x200, v4
	v_ashrrev_i32_e32 v233, 10, v232
	v_and_b32_e32 v232, 0x3ff, v232
	v_mul_u32_u24_e32 v227, 0x50, v232
	v_lshl_add_u32 v215, v233, 2, v227
	v_add_u32_e32 v233, s22, v233
	v_cmp_lt_i32_e64 s[20:21], 3, v233
	v_lshl_or_b32 v194, v233, 10, v232
	v_mov_b32_e32 v195, 0
	v_cndmask_b32_e64 v196, v182, v184, s[20:21]
	v_cndmask_b32_e64 v197, v183, v185, s[20:21]
	v_lshl_add_u64 v[196:197], v[194:195], 2, v[196:197]
	global_load_dword v221, v[196:197], off
	v_add_u32_e32 v232, 0x400, v4
	v_ashrrev_i32_e32 v233, 10, v232
	v_and_b32_e32 v232, 0x3ff, v232
	v_mul_u32_u24_e32 v228, 0x50, v232
	v_lshl_add_u32 v216, v233, 2, v228
	v_add_u32_e32 v233, s22, v233
	v_cmp_lt_i32_e64 s[20:21], 3, v233
	v_lshl_or_b32 v198, v233, 10, v232
	v_mov_b32_e32 v199, 0
	v_cndmask_b32_e64 v200, v182, v184, s[20:21]
	v_cndmask_b32_e64 v201, v183, v185, s[20:21]
	v_lshl_add_u64 v[200:201], v[198:199], 2, v[200:201]
	global_load_dword v222, v[200:201], off
	v_add_u32_e32 v232, 0x600, v4
	v_ashrrev_i32_e32 v233, 10, v232
	v_and_b32_e32 v232, 0x3ff, v232
	v_mul_u32_u24_e32 v229, 0x50, v232
	v_lshl_add_u32 v217, v233, 2, v229
	v_add_u32_e32 v233, s22, v233
	v_cmp_lt_i32_e64 s[20:21], 3, v233
	v_lshl_or_b32 v202, v233, 10, v232
	v_mov_b32_e32 v203, 0
	v_cndmask_b32_e64 v204, v182, v184, s[20:21]
	v_cndmask_b32_e64 v205, v183, v185, s[20:21]
	v_lshl_add_u64 v[204:205], v[202:203], 2, v[204:205]
	global_load_dword v223, v[204:205], off
	v_add_u32_e32 v232, 0x800, v4
	v_ashrrev_i32_e32 v233, 10, v232
	v_and_b32_e32 v232, 0x3ff, v232
	v_mul_u32_u24_e32 v230, 0x50, v232
	v_lshl_add_u32 v218, v233, 2, v230
	v_add_u32_e32 v233, s22, v233
	v_cmp_lt_i32_e64 s[20:21], 3, v233
	v_lshl_or_b32 v206, v233, 10, v232
	v_mov_b32_e32 v207, 0
	v_cndmask_b32_e64 v208, v182, v184, s[20:21]
	v_cndmask_b32_e64 v209, v183, v185, s[20:21]
	v_lshl_add_u64 v[208:209], v[206:207], 2, v[208:209]
	global_load_dword v224, v[208:209], off
	v_add_u32_e32 v232, 0xa00, v4
	v_ashrrev_i32_e32 v233, 10, v232
	v_and_b32_e32 v232, 0x3ff, v232
	v_mul_u32_u24_e32 v231, 0x50, v232
	v_lshl_add_u32 v219, v233, 2, v231
	v_add_u32_e32 v233, s22, v233
	v_cmp_lt_i32_e64 s[20:21], 3, v233
	v_lshl_or_b32 v210, v233, 10, v232
	v_mov_b32_e32 v211, 0
	v_cndmask_b32_e64 v212, v182, v184, s[20:21]
	v_cndmask_b32_e64 v213, v183, v185, s[20:21]
	v_lshl_add_u64 v[212:213], v[210:211], 2, v[212:213]
	global_load_dword v225, v[212:213], off
	s_waitcnt vmcnt(5)
	v_mul_f32_e32 v226, 0xbfb8aa3b, v220
	v_exp_f32_e32 v226, v226
	s_waitcnt vmcnt(4)
	v_mul_f32_e32 v227, 0xbfb8aa3b, v221
	v_exp_f32_e32 v227, v227
	s_waitcnt vmcnt(3)
	v_mul_f32_e32 v228, 0xbfb8aa3b, v222
	v_exp_f32_e32 v228, v228
	s_waitcnt vmcnt(2)
	v_mul_f32_e32 v229, 0xbfb8aa3b, v223
	v_exp_f32_e32 v229, v229
	s_waitcnt vmcnt(1)
	v_mul_f32_e32 v230, 0xbfb8aa3b, v224
	v_exp_f32_e32 v230, v230
	s_waitcnt vmcnt(0)
	v_mul_f32_e32 v231, 0xbfb8aa3b, v225
	v_exp_f32_e32 v231, v231
	s_nop 0
	v_add_f32_e32 v226, 1.0, v226
	v_add_f32_e32 v227, 1.0, v227
	v_add_f32_e32 v228, 1.0, v228
	v_add_f32_e32 v229, 1.0, v229
	v_add_f32_e32 v230, 1.0, v230
	v_add_f32_e32 v231, 1.0, v231
	v_rcp_f32_e32 v226, v226
	v_rcp_f32_e32 v227, v227
	v_rcp_f32_e32 v228, v228
	v_rcp_f32_e32 v229, v229
	v_rcp_f32_e32 v230, v230
	v_rcp_f32_e32 v231, v231
	s_nop 0
	v_mul_f32_e32 v220, v220, v226
	v_mul_f32_e32 v221, v221, v227
	v_mul_f32_e32 v222, v222, v228
	v_mul_f32_e32 v223, v223, v229
	v_mul_f32_e32 v224, v224, v230
	v_mul_f32_e32 v225, v225, v231
	ds_write_b32 v214, v220
	ds_write_b32 v215, v221
	ds_write_b32 v216, v222
	ds_write_b32 v217, v223
	ds_write_b32 v218, v224
	ds_write_b32 v219, v225
	v_add_u32_e32 v4, 0xc00, v4
	s_add_i32 s98, s98, 1
	s_cmp_lt_u32 s98, 6
	s_cbranch_scc1 .Lsilu_outer

.Lp0w_begin:
	v_mov_b32_e32 v194, v4
	v_mov_b32_e32 v195, v5
	v_add_co_u32_e64 v24, s[4:5], s36, v4
	global_load_dword v0, v[4:5], off
	s_nop 0
	v_addc_co_u32_e64 v25, s[4:5], -1, v5, s[4:5]
	v_add_co_u32_e64 v26, s[4:5], s37, v4
	s_nop 1
	v_addc_co_u32_e64 v27, s[4:5], -1, v5, s[4:5]
	v_add_co_u32_e64 v28, s[4:5], s38, v4
	s_nop 1
	v_addc_co_u32_e64 v29, s[4:5], -1, v5, s[4:5]
	v_add_co_u32_e64 v30, s[4:5], s39, v4
	s_nop 1
	v_addc_co_u32_e64 v31, s[4:5], -1, v5, s[4:5]
	v_add_co_u32_e64 v32, s[4:5], s40, v4
	s_nop 1
	v_addc_co_u32_e64 v33, s[4:5], -1, v5, s[4:5]
	v_add_co_u32_e64 v34, s[4:5], s41, v4
	s_nop 1
	v_addc_co_u32_e64 v35, s[4:5], -1, v5, s[4:5]
	v_add_co_u32_e64 v36, s[4:5], s42, v4
	s_nop 1
	v_addc_co_u32_e64 v37, s[4:5], -1, v5, s[4:5]
	global_load_dword v174, v[24:25], off
	global_load_dword v175, v[26:27], off
	global_load_dword v177, v[30:31], off
	global_load_dword v179, v[34:35], off
	global_load_dword v176, v[28:29], off
	global_load_dword v178, v[32:33], off
	global_load_dword v36, v[36:37], off
	v_lshl_add_u64 v[4:5], v[4:5], 0, s[16:17]
.LBB0_24:
	v_add_co_u32_e64 v24, s[4:5], s36, v4
	global_load_dword v182, v[4:5], off
	s_nop 0
	v_addc_co_u32_e64 v25, s[4:5], -1, v5, s[4:5]
	v_add_co_u32_e64 v26, s[4:5], s37, v4
	s_nop 1
	v_addc_co_u32_e64 v27, s[4:5], -1, v5, s[4:5]
	v_add_co_u32_e64 v28, s[4:5], s38, v4
	s_nop 1
	v_addc_co_u32_e64 v29, s[4:5], -1, v5, s[4:5]
	v_add_co_u32_e64 v30, s[4:5], s39, v4
	s_nop 1
	v_addc_co_u32_e64 v31, s[4:5], -1, v5, s[4:5]
	v_add_co_u32_e64 v32, s[4:5], s40, v4
	s_nop 1
	v_addc_co_u32_e64 v33, s[4:5], -1, v5, s[4:5]
	v_add_co_u32_e64 v34, s[4:5], s41, v4
	s_nop 1
	v_addc_co_u32_e64 v35, s[4:5], -1, v5, s[4:5]
	v_add_co_u32_e64 v192, s[4:5], s42, v4
	s_nop 1
	v_addc_co_u32_e64 v193, s[4:5], -1, v5, s[4:5]
	global_load_dword v184, v[24:25], off
	global_load_dword v185, v[26:27], off
	global_load_dword v187, v[30:31], off
	global_load_dword v189, v[34:35], off
	global_load_dword v186, v[28:29], off
	global_load_dword v188, v[32:33], off
	global_load_dword v190, v[192:193], off
	v_lshl_add_u64 v[4:5], v[4:5], 0, s[16:17]
	v_mov_b32_e32 v170, s19
	s_addk_i32 s19, 0x280
	ds_read_b128 v[24:27], v170
	ds_read_b128 v[28:31], v170 offset:16
	ds_read_b128 v[32:35], v170 offset:32
	ds_read_b128 v[42:45], v170 offset:48
	ds_read2_b64 v[46:49], v170 offset0:8 offset1:18
	ds_read_b128 v[50:53], v170 offset:80
	ds_read_b128 v[54:57], v170 offset:96
	ds_read_b128 v[58:61], v170 offset:112
	ds_read_b128 v[62:65], v170 offset:128
	ds_read_b128 v[66:69], v170 offset:160
	ds_read_b128 v[70:73], v170 offset:176
	ds_read_b128 v[74:77], v170 offset:192
	ds_read_b128 v[78:81], v170 offset:208
	ds_read2_b64 v[82:85], v170 offset0:28 offset1:38
	ds_read_b128 v[86:89], v170 offset:240
	ds_read_b128 v[90:93], v170 offset:256
	ds_read_b128 v[94:97], v170 offset:272
	ds_read_b128 v[98:101], v170 offset:288
	ds_read_b128 v[102:105], v170 offset:320
	ds_read_b128 v[106:109], v170 offset:336
	ds_read_b128 v[110:113], v170 offset:352
	ds_read_b128 v[114:117], v170 offset:368
	ds_read2_b64 v[118:121], v170 offset0:48 offset1:58
	ds_read_b128 v[122:125], v170 offset:400
	ds_read_b128 v[126:129], v170 offset:416
	ds_read_b128 v[130:133], v170 offset:432
	ds_read_b128 v[134:137], v170 offset:448
	ds_read_b128 v[138:141], v170 offset:480
	ds_read_b128 v[142:145], v170 offset:496
	ds_read_b128 v[146:149], v170 offset:512
	ds_read_b128 v[150:153], v170 offset:528
	ds_read2_b64 v[154:157], v170 offset0:68 offset1:78
	ds_read_b128 v[158:161], v170 offset:560
	ds_read_b128 v[162:165], v170 offset:576
	ds_read_b128 v[166:169], v170 offset:592
	ds_read_b128 v[170:173], v170 offset:608
	s_waitcnt vmcnt(15) lgkmcnt(4)
	v_mul_f32_e32 v180, v0, v156
	v_mov_b32_e32 v156, v155
	s_waitcnt vmcnt(13)
	v_pk_fma_f32 v[8:9], v[174:175], v[24:25], v[8:9] op_sel_hi:[0,1,1]
	v_pk_fma_f32 v[10:11], v[174:175], v[26:27], v[10:11] op_sel_hi:[0,1,1]
	v_pk_fma_f32 v[12:13], v[174:175], v[28:29], v[12:13] op_sel_hi:[0,1,1]
	v_pk_fma_f32 v[14:15], v[174:175], v[30:31], v[14:15] op_sel_hi:[0,1,1]
	v_pk_fma_f32 v[16:17], v[174:175], v[32:33], v[16:17] op_sel_hi:[0,1,1]
	v_pk_fma_f32 v[18:19], v[174:175], v[34:35], v[18:19] op_sel_hi:[0,1,1]
	v_pk_fma_f32 v[20:21], v[174:175], v[42:43], v[20:21] op_sel_hi:[0,1,1]
	v_pk_fma_f32 v[22:23], v[174:175], v[44:45], v[22:23] op_sel_hi:[0,1,1]
	v_mov_b32_e32 v24, v175
	v_mul_f32_e32 v32, v175, v48
	v_mov_b32_e32 v48, v47
	v_pk_fma_f32 v[8:9], v[24:25], v[50:51], v[8:9] op_sel_hi:[0,1,1]
	v_pk_fma_f32 v[10:11], v[24:25], v[52:53], v[10:11] op_sel_hi:[0,1,1]
	v_pk_fma_f32 v[12:13], v[24:25], v[54:55], v[12:13] op_sel_hi:[0,1,1]
	v_pk_fma_f32 v[14:15], v[24:25], v[56:57], v[14:15] op_sel_hi:[0,1,1]
	v_pk_fma_f32 v[16:17], v[24:25], v[58:59], v[16:17] op_sel_hi:[0,1,1]
	v_pk_fma_f32 v[18:19], v[24:25], v[60:61], v[18:19] op_sel_hi:[0,1,1]
	v_pk_fma_f32 v[20:21], v[24:25], v[62:63], v[20:21] op_sel_hi:[0,1,1]
	v_pk_fma_f32 v[22:23], v[24:25], v[64:65], v[22:23] op_sel_hi:[0,1,1]
	v_pk_mul_f32 v[24:25], v[174:175], v[48:49]
	s_waitcnt vmcnt(12)
	v_mov_b32_e32 v26, v177
	v_mul_f32_e32 v30, v174, v46
	v_mul_f32_e32 v42, v177, v84
	v_mov_b32_e32 v84, v83
	s_waitcnt vmcnt(10)
	v_pk_fma_f32 v[8:9], v[176:177], v[66:67], v[8:9] op_sel_hi:[0,1,1]
	v_pk_fma_f32 v[10:11], v[176:177], v[68:69], v[10:11] op_sel_hi:[0,1,1]
	v_pk_fma_f32 v[12:13], v[176:177], v[70:71], v[12:13] op_sel_hi:[0,1,1]
	v_pk_fma_f32 v[14:15], v[176:177], v[72:73], v[14:15] op_sel_hi:[0,1,1]
	v_pk_fma_f32 v[16:17], v[176:177], v[74:75], v[16:17] op_sel_hi:[0,1,1]
	v_pk_fma_f32 v[18:19], v[176:177], v[76:77], v[18:19] op_sel_hi:[0,1,1]
	v_pk_fma_f32 v[20:21], v[176:177], v[78:79], v[20:21] op_sel_hi:[0,1,1]
	v_pk_fma_f32 v[22:23], v[176:177], v[80:81], v[22:23] op_sel_hi:[0,1,1]
	v_mov_b32_e32 v31, v24
	v_pk_mul_f32 v[48:49], v[176:177], v[84:85]
	v_mov_b32_e32 v33, v25
	v_pk_fma_f32 v[8:9], v[26:27], v[86:87], v[8:9] op_sel_hi:[0,1,1]
	v_pk_fma_f32 v[10:11], v[26:27], v[88:89], v[10:11] op_sel_hi:[0,1,1]
	v_pk_fma_f32 v[12:13], v[26:27], v[90:91], v[12:13] op_sel_hi:[0,1,1]
	v_pk_fma_f32 v[14:15], v[26:27], v[92:93], v[14:15] op_sel_hi:[0,1,1]
	v_pk_fma_f32 v[16:17], v[26:27], v[94:95], v[16:17] op_sel_hi:[0,1,1]
	v_pk_fma_f32 v[18:19], v[26:27], v[96:97], v[18:19] op_sel_hi:[0,1,1]
	v_pk_fma_f32 v[20:21], v[26:27], v[98:99], v[20:21] op_sel_hi:[0,1,1]
	v_pk_fma_f32 v[22:23], v[26:27], v[100:101], v[22:23] op_sel_hi:[0,1,1]
	v_pk_add_f32 v[6:7], v[6:7], v[30:31]
	v_mov_b32_e32 v28, v179
	v_mul_f32_e32 v34, v176, v82
	v_mul_f32_e32 v46, v179, v120
	v_mov_b32_e32 v120, v119
	v_mov_b32_e32 v35, v48
	s_waitcnt vmcnt(9)
	v_pk_fma_f32 v[8:9], v[178:179], v[102:103], v[8:9] op_sel_hi:[0,1,1]
	v_pk_fma_f32 v[10:11], v[178:179], v[104:105], v[10:11] op_sel_hi:[0,1,1]
	v_pk_fma_f32 v[12:13], v[178:179], v[106:107], v[12:13] op_sel_hi:[0,1,1]
	v_pk_fma_f32 v[14:15], v[178:179], v[108:109], v[14:15] op_sel_hi:[0,1,1]
	v_pk_fma_f32 v[16:17], v[178:179], v[110:111], v[16:17] op_sel_hi:[0,1,1]
	v_pk_fma_f32 v[18:19], v[178:179], v[112:113], v[18:19] op_sel_hi:[0,1,1]
	v_pk_fma_f32 v[20:21], v[178:179], v[114:115], v[20:21] op_sel_hi:[0,1,1]
	v_pk_fma_f32 v[22:23], v[178:179], v[116:117], v[22:23] op_sel_hi:[0,1,1]
	v_pk_add_f32 v[6:7], v[6:7], v[32:33]
	v_pk_mul_f32 v[50:51], v[178:179], v[120:121]
	v_mov_b32_e32 v43, v49
	v_pk_fma_f32 v[8:9], v[28:29], v[122:123], v[8:9] op_sel_hi:[0,1,1]
	v_pk_fma_f32 v[10:11], v[28:29], v[124:125], v[10:11] op_sel_hi:[0,1,1]
	v_pk_fma_f32 v[12:13], v[28:29], v[126:127], v[12:13] op_sel_hi:[0,1,1]
	v_pk_fma_f32 v[14:15], v[28:29], v[128:129], v[14:15] op_sel_hi:[0,1,1]
	v_pk_fma_f32 v[16:17], v[28:29], v[130:131], v[16:17] op_sel_hi:[0,1,1]
	v_pk_fma_f32 v[18:19], v[28:29], v[132:133], v[18:19] op_sel_hi:[0,1,1]
	v_pk_fma_f32 v[20:21], v[28:29], v[134:135], v[20:21] op_sel_hi:[0,1,1]
	v_pk_fma_f32 v[22:23], v[28:29], v[136:137], v[22:23] op_sel_hi:[0,1,1]
	v_pk_add_f32 v[6:7], v[6:7], v[34:35]
	v_mul_f32_e32 v44, v178, v118
	v_mov_b32_e32 v45, v50
	s_waitcnt vmcnt(8)
	v_pk_fma_f32 v[8:9], v[36:37], v[138:139], v[8:9] op_sel_hi:[0,1,1]
	v_pk_fma_f32 v[10:11], v[36:37], v[140:141], v[10:11] op_sel_hi:[0,1,1]
	v_pk_fma_f32 v[12:13], v[36:37], v[142:143], v[12:13] op_sel_hi:[0,1,1]
	v_pk_fma_f32 v[14:15], v[36:37], v[144:145], v[14:15] op_sel_hi:[0,1,1]
	v_pk_fma_f32 v[16:17], v[36:37], v[146:147], v[16:17] op_sel_hi:[0,1,1]
	v_pk_fma_f32 v[18:19], v[36:37], v[148:149], v[18:19] op_sel_hi:[0,1,1]
	v_pk_fma_f32 v[20:21], v[36:37], v[150:151], v[20:21] op_sel_hi:[0,1,1]
	v_pk_fma_f32 v[22:23], v[36:37], v[152:153], v[22:23] op_sel_hi:[0,1,1]
	v_mov_b32_e32 v37, v0
	v_pk_add_f32 v[6:7], v[6:7], v[42:43]
	v_mov_b32_e32 v47, v51
	v_pk_mul_f32 v[24:25], v[36:37], v[156:157]
	v_pk_add_f32 v[6:7], v[6:7], v[44:45]
	v_mul_f32_e32 v82, v36, v154
	v_pk_add_f32 v[6:7], v[6:7], v[46:47]
	v_mov_b32_e32 v83, v24
	v_mov_b32_e32 v181, v25
	v_pk_add_f32 v[6:7], v[6:7], v[82:83]
	s_waitcnt lgkmcnt(3)
	v_pk_fma_f32 v[8:9], v[0:1], v[158:159], v[8:9] op_sel_hi:[0,1,1]
	v_pk_fma_f32 v[10:11], v[0:1], v[160:161], v[10:11] op_sel_hi:[0,1,1]
	s_waitcnt lgkmcnt(2)
	v_pk_fma_f32 v[12:13], v[0:1], v[162:163], v[12:13] op_sel_hi:[0,1,1]
	v_pk_fma_f32 v[14:15], v[0:1], v[164:165], v[14:15] op_sel_hi:[0,1,1]
	s_waitcnt lgkmcnt(1)
	v_pk_fma_f32 v[16:17], v[0:1], v[166:167], v[16:17] op_sel_hi:[0,1,1]
	v_pk_fma_f32 v[18:19], v[0:1], v[168:169], v[18:19] op_sel_hi:[0,1,1]
	s_waitcnt lgkmcnt(0)
	v_pk_fma_f32 v[20:21], v[0:1], v[170:171], v[20:21] op_sel_hi:[0,1,1]
	v_pk_fma_f32 v[22:23], v[0:1], v[172:173], v[22:23] op_sel_hi:[0,1,1]
	v_pk_add_f32 v[6:7], v[6:7], v[180:181]
	s_cmpk_eq_i32 s18, 0x68
	s_cbranch_scc0 .Lp0w_noclamp
	v_mov_b32_e32 v4, v194
	v_mov_b32_e32 v5, v195
.Lp0w_noclamp:
	v_add_co_u32_e64 v24, s[4:5], s36, v4
	global_load_dword v0, v[4:5], off
	s_nop 0
	v_addc_co_u32_e64 v25, s[4:5], -1, v5, s[4:5]
	v_add_co_u32_e64 v26, s[4:5], s37, v4
	s_nop 1
	v_addc_co_u32_e64 v27, s[4:5], -1, v5, s[4:5]
	v_add_co_u32_e64 v28, s[4:5], s38, v4
	s_nop 1
	v_addc_co_u32_e64 v29, s[4:5], -1, v5, s[4:5]
	v_add_co_u32_e64 v30, s[4:5], s39, v4
	s_nop 1
	v_addc_co_u32_e64 v31, s[4:5], -1, v5, s[4:5]
	v_add_co_u32_e64 v32, s[4:5], s40, v4
	s_nop 1
	v_addc_co_u32_e64 v33, s[4:5], -1, v5, s[4:5]
	v_add_co_u32_e64 v34, s[4:5], s41, v4
	s_nop 1
	v_addc_co_u32_e64 v35, s[4:5], -1, v5, s[4:5]
	v_add_co_u32_e64 v36, s[4:5], s42, v4
	s_nop 1
	v_addc_co_u32_e64 v37, s[4:5], -1, v5, s[4:5]
	global_load_dword v174, v[24:25], off
	global_load_dword v175, v[26:27], off
	global_load_dword v177, v[30:31], off
	global_load_dword v179, v[34:35], off
	global_load_dword v176, v[28:29], off
	global_load_dword v178, v[32:33], off
	global_load_dword v36, v[36:37], off
	v_lshl_add_u64 v[4:5], v[4:5], 0, s[16:17]
	v_mov_b32_e32 v170, s19
	s_addk_i32 s19, 0x280
	ds_read_b128 v[24:27], v170
	ds_read_b128 v[28:31], v170 offset:16
	ds_read_b128 v[32:35], v170 offset:32
	ds_read_b128 v[42:45], v170 offset:48
	ds_read2_b64 v[46:49], v170 offset0:8 offset1:18
	ds_read_b128 v[50:53], v170 offset:80
	ds_read_b128 v[54:57], v170 offset:96
	ds_read_b128 v[58:61], v170 offset:112
	ds_read_b128 v[62:65], v170 offset:128
	ds_read_b128 v[66:69], v170 offset:160
	ds_read_b128 v[70:73], v170 offset:176
	ds_read_b128 v[74:77], v170 offset:192
	ds_read_b128 v[78:81], v170 offset:208
	ds_read2_b64 v[82:85], v170 offset0:28 offset1:38
	ds_read_b128 v[86:89], v170 offset:240
	ds_read_b128 v[90:93], v170 offset:256
	ds_read_b128 v[94:97], v170 offset:272
	ds_read_b128 v[98:101], v170 offset:288
	ds_read_b128 v[102:105], v170 offset:320
	ds_read_b128 v[106:109], v170 offset:336
	ds_read_b128 v[110:113], v170 offset:352
	ds_read_b128 v[114:117], v170 offset:368
	ds_read2_b64 v[118:121], v170 offset0:48 offset1:58
	ds_read_b128 v[122:125], v170 offset:400
	ds_read_b128 v[126:129], v170 offset:416
	ds_read_b128 v[130:133], v170 offset:432
	ds_read_b128 v[134:137], v170 offset:448
	ds_read_b128 v[138:141], v170 offset:480
	ds_read_b128 v[142:145], v170 offset:496
	ds_read_b128 v[146:149], v170 offset:512
	ds_read_b128 v[150:153], v170 offset:528
	ds_read2_b64 v[154:157], v170 offset0:68 offset1:78
	ds_read_b128 v[158:161], v170 offset:560
	ds_read_b128 v[162:165], v170 offset:576
	ds_read_b128 v[166:169], v170 offset:592
	ds_read_b128 v[170:173], v170 offset:608
	s_waitcnt vmcnt(15) lgkmcnt(4)
	v_mul_f32_e32 v180, v182, v156
	v_mov_b32_e32 v156, v155
	s_waitcnt vmcnt(13)
	v_pk_fma_f32 v[8:9], v[184:185], v[24:25], v[8:9] op_sel_hi:[0,1,1]
	v_pk_fma_f32 v[10:11], v[184:185], v[26:27], v[10:11] op_sel_hi:[0,1,1]
	v_pk_fma_f32 v[12:13], v[184:185], v[28:29], v[12:13] op_sel_hi:[0,1,1]
	v_pk_fma_f32 v[14:15], v[184:185], v[30:31], v[14:15] op_sel_hi:[0,1,1]
	v_pk_fma_f32 v[16:17], v[184:185], v[32:33], v[16:17] op_sel_hi:[0,1,1]
	v_pk_fma_f32 v[18:19], v[184:185], v[34:35], v[18:19] op_sel_hi:[0,1,1]
	v_pk_fma_f32 v[20:21], v[184:185], v[42:43], v[20:21] op_sel_hi:[0,1,1]
	v_pk_fma_f32 v[22:23], v[184:185], v[44:45], v[22:23] op_sel_hi:[0,1,1]
	v_mov_b32_e32 v24, v185
	v_mul_f32_e32 v32, v185, v48
	v_mov_b32_e32 v48, v47
	v_pk_fma_f32 v[8:9], v[24:25], v[50:51], v[8:9] op_sel_hi:[0,1,1]
	v_pk_fma_f32 v[10:11], v[24:25], v[52:53], v[10:11] op_sel_hi:[0,1,1]
	v_pk_fma_f32 v[12:13], v[24:25], v[54:55], v[12:13] op_sel_hi:[0,1,1]
	v_pk_fma_f32 v[14:15], v[24:25], v[56:57], v[14:15] op_sel_hi:[0,1,1]
	v_pk_fma_f32 v[16:17], v[24:25], v[58:59], v[16:17] op_sel_hi:[0,1,1]
	v_pk_fma_f32 v[18:19], v[24:25], v[60:61], v[18:19] op_sel_hi:[0,1,1]
	v_pk_fma_f32 v[20:21], v[24:25], v[62:63], v[20:21] op_sel_hi:[0,1,1]
	v_pk_fma_f32 v[22:23], v[24:25], v[64:65], v[22:23] op_sel_hi:[0,1,1]
	v_pk_mul_f32 v[24:25], v[184:185], v[48:49]
	s_waitcnt vmcnt(12)
	v_mov_b32_e32 v26, v187
	v_mul_f32_e32 v30, v184, v46
	v_mul_f32_e32 v42, v187, v84
	v_mov_b32_e32 v84, v83
	s_waitcnt vmcnt(10)
	v_pk_fma_f32 v[8:9], v[186:187], v[66:67], v[8:9] op_sel_hi:[0,1,1]
	v_pk_fma_f32 v[10:11], v[186:187], v[68:69], v[10:11] op_sel_hi:[0,1,1]
	v_pk_fma_f32 v[12:13], v[186:187], v[70:71], v[12:13] op_sel_hi:[0,1,1]
	v_pk_fma_f32 v[14:15], v[186:187], v[72:73], v[14:15] op_sel_hi:[0,1,1]
	v_pk_fma_f32 v[16:17], v[186:187], v[74:75], v[16:17] op_sel_hi:[0,1,1]
	v_pk_fma_f32 v[18:19], v[186:187], v[76:77], v[18:19] op_sel_hi:[0,1,1]
	v_pk_fma_f32 v[20:21], v[186:187], v[78:79], v[20:21] op_sel_hi:[0,1,1]
	v_pk_fma_f32 v[22:23], v[186:187], v[80:81], v[22:23] op_sel_hi:[0,1,1]
	v_mov_b32_e32 v31, v24
	v_pk_mul_f32 v[48:49], v[186:187], v[84:85]
	v_mov_b32_e32 v33, v25
	v_pk_fma_f32 v[8:9], v[26:27], v[86:87], v[8:9] op_sel_hi:[0,1,1]
	v_pk_fma_f32 v[10:11], v[26:27], v[88:89], v[10:11] op_sel_hi:[0,1,1]
	v_pk_fma_f32 v[12:13], v[26:27], v[90:91], v[12:13] op_sel_hi:[0,1,1]
	v_pk_fma_f32 v[14:15], v[26:27], v[92:93], v[14:15] op_sel_hi:[0,1,1]
	v_pk_fma_f32 v[16:17], v[26:27], v[94:95], v[16:17] op_sel_hi:[0,1,1]
	v_pk_fma_f32 v[18:19], v[26:27], v[96:97], v[18:19] op_sel_hi:[0,1,1]
	v_pk_fma_f32 v[20:21], v[26:27], v[98:99], v[20:21] op_sel_hi:[0,1,1]
	v_pk_fma_f32 v[22:23], v[26:27], v[100:101], v[22:23] op_sel_hi:[0,1,1]
	v_pk_add_f32 v[6:7], v[6:7], v[30:31]
	v_mov_b32_e32 v28, v189
	v_mul_f32_e32 v34, v186, v82
	v_mul_f32_e32 v46, v189, v120
	v_mov_b32_e32 v120, v119
	v_mov_b32_e32 v35, v48
	s_waitcnt vmcnt(9)
	v_pk_fma_f32 v[8:9], v[188:189], v[102:103], v[8:9] op_sel_hi:[0,1,1]
	v_pk_fma_f32 v[10:11], v[188:189], v[104:105], v[10:11] op_sel_hi:[0,1,1]
	v_pk_fma_f32 v[12:13], v[188:189], v[106:107], v[12:13] op_sel_hi:[0,1,1]
	v_pk_fma_f32 v[14:15], v[188:189], v[108:109], v[14:15] op_sel_hi:[0,1,1]
	v_pk_fma_f32 v[16:17], v[188:189], v[110:111], v[16:17] op_sel_hi:[0,1,1]
	v_pk_fma_f32 v[18:19], v[188:189], v[112:113], v[18:19] op_sel_hi:[0,1,1]
	v_pk_fma_f32 v[20:21], v[188:189], v[114:115], v[20:21] op_sel_hi:[0,1,1]
	v_pk_fma_f32 v[22:23], v[188:189], v[116:117], v[22:23] op_sel_hi:[0,1,1]
	v_pk_add_f32 v[6:7], v[6:7], v[32:33]
	v_pk_mul_f32 v[50:51], v[188:189], v[120:121]
	v_mov_b32_e32 v43, v49
	v_pk_fma_f32 v[8:9], v[28:29], v[122:123], v[8:9] op_sel_hi:[0,1,1]
	v_pk_fma_f32 v[10:11], v[28:29], v[124:125], v[10:11] op_sel_hi:[0,1,1]
	v_pk_fma_f32 v[12:13], v[28:29], v[126:127], v[12:13] op_sel_hi:[0,1,1]
	v_pk_fma_f32 v[14:15], v[28:29], v[128:129], v[14:15] op_sel_hi:[0,1,1]
	v_pk_fma_f32 v[16:17], v[28:29], v[130:131], v[16:17] op_sel_hi:[0,1,1]
	v_pk_fma_f32 v[18:19], v[28:29], v[132:133], v[18:19] op_sel_hi:[0,1,1]
	v_pk_fma_f32 v[20:21], v[28:29], v[134:135], v[20:21] op_sel_hi:[0,1,1]
	v_pk_fma_f32 v[22:23], v[28:29], v[136:137], v[22:23] op_sel_hi:[0,1,1]
	v_pk_add_f32 v[6:7], v[6:7], v[34:35]
	v_mul_f32_e32 v44, v188, v118
	v_mov_b32_e32 v45, v50
	s_waitcnt vmcnt(8)
	v_pk_fma_f32 v[8:9], v[190:191], v[138:139], v[8:9] op_sel_hi:[0,1,1]
	v_pk_fma_f32 v[10:11], v[190:191], v[140:141], v[10:11] op_sel_hi:[0,1,1]
	v_pk_fma_f32 v[12:13], v[190:191], v[142:143], v[12:13] op_sel_hi:[0,1,1]
	v_pk_fma_f32 v[14:15], v[190:191], v[144:145], v[14:15] op_sel_hi:[0,1,1]
	v_pk_fma_f32 v[16:17], v[190:191], v[146:147], v[16:17] op_sel_hi:[0,1,1]
	v_pk_fma_f32 v[18:19], v[190:191], v[148:149], v[18:19] op_sel_hi:[0,1,1]
	v_pk_fma_f32 v[20:21], v[190:191], v[150:151], v[20:21] op_sel_hi:[0,1,1]
	v_pk_fma_f32 v[22:23], v[190:191], v[152:153], v[22:23] op_sel_hi:[0,1,1]
	v_mov_b32_e32 v191, v182
	v_pk_add_f32 v[6:7], v[6:7], v[42:43]
	v_mov_b32_e32 v47, v51
	v_pk_mul_f32 v[24:25], v[190:191], v[156:157]
	v_pk_add_f32 v[6:7], v[6:7], v[44:45]
	v_mul_f32_e32 v82, v190, v154
	v_pk_add_f32 v[6:7], v[6:7], v[46:47]
	v_mov_b32_e32 v83, v24
	v_mov_b32_e32 v181, v25
	v_pk_add_f32 v[6:7], v[6:7], v[82:83]
	s_waitcnt lgkmcnt(3)
	v_pk_fma_f32 v[8:9], v[182:183], v[158:159], v[8:9] op_sel_hi:[0,1,1]
	v_pk_fma_f32 v[10:11], v[182:183], v[160:161], v[10:11] op_sel_hi:[0,1,1]
	s_waitcnt lgkmcnt(2)
	v_pk_fma_f32 v[12:13], v[182:183], v[162:163], v[12:13] op_sel_hi:[0,1,1]
	v_pk_fma_f32 v[14:15], v[182:183], v[164:165], v[14:15] op_sel_hi:[0,1,1]
	s_waitcnt lgkmcnt(1)
	v_pk_fma_f32 v[16:17], v[182:183], v[166:167], v[16:17] op_sel_hi:[0,1,1]
	v_pk_fma_f32 v[18:19], v[182:183], v[168:169], v[18:19] op_sel_hi:[0,1,1]
	s_waitcnt lgkmcnt(0)
	v_pk_fma_f32 v[20:21], v[182:183], v[170:171], v[20:21] op_sel_hi:[0,1,1]
	v_pk_fma_f32 v[22:23], v[182:183], v[172:173], v[22:23] op_sel_hi:[0,1,1]
	v_pk_add_f32 v[6:7], v[6:7], v[180:181]
	s_add_i32 s18, s18, 16
	s_cmpk_lt_i32 s18, 0x78
	s_cbranch_scc1 .LBB0_24
	s_waitcnt vmcnt(0)
.Lp0w_end:
	v_add_u32_e32 v0, s24, v41
	ds_write2st64_b32 v0, v8, v9 offset1:1
	ds_write2st64_b32 v0, v10, v11 offset0:2 offset1:3
	ds_write2st64_b32 v0, v12, v13 offset0:4 offset1:5
	ds_write2st64_b32 v0, v14, v15 offset0:6 offset1:7
	ds_write2st64_b32 v0, v16, v17 offset0:8 offset1:9
	ds_write2st64_b32 v0, v18, v19 offset0:10 offset1:11
	ds_write2st64_b32 v0, v20, v21 offset0:12 offset1:13
	ds_write2st64_b32 v0, v22, v23 offset0:14 offset1:15
	ds_write2st64_b32 v0, v6, v7 offset0:16 offset1:17
	s_waitcnt lgkmcnt(0)
	s_barrier
	s_and_saveexec_b64 s[18:19], s[2:3]
	s_cbranch_execz .LBB0_15
	s_mul_i32 s4, s20, 0x1800
	s_mul_hi_i32 s5, s20, 36
	s_mul_i32 s20, s20, 36
	v_add_u32_e32 v4, s4, v2
	s_add_u32 s20, s20, s22
	v_ashrrev_i32_e32 v5, 31, v4
	s_addc_u32 s21, s5, 0
	v_lshl_add_u64 v[4:5], v[4:5], 2, s[12:13]
	v_lshl_add_u64 v[2:3], v[2:3], 2, s[14:15]
	s_mov_b64 s[22:23], 0
	v_mov_b32_e32 v0, v40
